# v36 + residual-GEMM tail tiles split into two M-half units on CUs x and x+8 of the same XCD (MFMA blocks, A reads and stores of the other half skipped); L2 warm-up helpers moved to CUs 16..79, pre-run
# speedup vs baseline: 1.0034x; 1.0034x over previous
;     __host__ __device__ bool next(int i, Unit& u) const {
;     ...
;         int wgid = (int)L; { const int q = nwg / NXCD, r = nwg % NXCD, xcd = wgid % NXCD, off = wgid / NXCD; wgid = (xcd < r ? xcd * (q + 1) : r * (q + 1) + (xcd - r) * q) + off; }
;         const int nig = WGM * nN, gid = wgid / nig, fm = gid * WGM, gsz = (nM - fm) < WGM ? (nM - fm) : WGM;
;         u.pm = fm + ((wgid % nig) % gsz); u.pn = (wgid % nig) / gsz; return true;
.Lpre_real:
	s_movk_i32 s98, 0xb00
	s_and_b32 s100, s96, 7
	s_cmp_gt_u32 s100, 2
	s_cbranch_scc1 .Lpre_done
	s_lshr_b32 s101, s96, 3
	s_add_i32 s101, s101, -10
	s_cmp_gt_u32 s101, 21
	s_cbranch_scc1 .Lpre_done
	s_mul_i32 s101, s101, 3
	s_add_i32 s101, s101, s100
	s_and_b32 s100, s101, 7
	s_lshr_b32 s101, s101, 3
	s_addk_i32 s101, 0x160
	s_mul_i32 s2, s100, 0x168
	s_min_u32 s100, s100, 2
	s_add_i32 s2, s2, s100
	s_add_i32 s2, s2, s101
	s_mul_hi_u32 s23, s2, 0x2e8ba2e9
	s_lshr_b32 s23, s23, 5
	s_mul_i32 s100, s23, 0xb0
	s_sub_i32 s100, s2, s100
	s_lshl_b32 s23, s23, 3
	s_cmp_eq_u32 s23, 0x80
	s_cbranch_scc1 .Lpre_g16
	s_and_b32 s2, s100, 7
	s_add_i32 s2, s2, s23
	s_lshr_b32 s23, s100, 3
	s_branch .Lpre_done

;     __host__ __device__ bool next(int i, Unit& u) const {
;         const long L = (long)i * G + c; if (L >= nwg) return false;
;         int wgid = (int)L; { const int q = nwg / NXCD, r = nwg % NXCD, xcd = wgid % NXCD, off = wgid / NXCD; wgid = (xcd < r ? xcd * (q + 1) : r * (q + 1) + (xcd - r) * q) + off; }
;         const int nig = WGM * nN, gid = wgid / nig, fm = gid * WGM, gsz = (nM - fm) < WGM ? (nM - fm) : WGM;
;         u.pm = fm + ((wgid % nig) % gsz); u.pn = (wgid % nig) / gsz; return true;
; template <class Epi, class Sched, bool ALIGN_EPI = false, bool SP2 = false>
; __device__ __forceinline__ void gemm_phase(PG8_LAS unsigned char* lds, const Gemm g, const Sched& S, const Epi& E, int tid_in) {
;     ...
;         const bool has_next = S.next(ui + 1, nxt);
.LBB0_530:
	s_add_i32 s71, s71, 1
	s_mul_i32 s12, s71, s87
	s_mul_hi_u32 s13, s71, s94
	s_add_i32 s13, s13, s12
	s_mul_i32 s12, s71, s94
	s_add_u32 s12, s12, s96
	s_addc_u32 s13, s13, s97
	s_mov_b32 s100, 0
	s_cmp_lg_u32 s94, 0x100
	s_cbranch_scc1 .Lhalf_sched_done
	s_lshr_b32 s101, s20, 8
	s_cmp_lg_u32 s71, s101
	s_cbranch_scc1 .Lhalf_sched_done
	s_and_b32 s101, s20, 0xff
	s_mov_b32 s12, s20
	s_mov_b32 s13, 0
	s_cmp_gt_u32 s96, 15
	s_cbranch_scc1 .Lhalf_sched_done
	s_and_b32 s100, s96, 7
	s_cmp_ge_u32 s100, s101
	s_mov_b32 s100, 0
	s_cbranch_scc1 .Lhalf_sched_done
	s_and_b32 s12, s96, 7
	s_andn2_b32 s101, s20, 0xff
	s_add_i32 s12, s12, s101
	s_lshr_b32 s100, s96, 3
	s_add_i32 s100, s100, 1

; #define PG8_STAGE(bufoff, gbase, voff) do { _Pragma("unroll") for (int _i = 0; _i < 2; ++_i) \
;         __builtin_amdgcn_global_load_lds((const unsigned*)((const char*)(gbase) + (voff)[_i]), (PG8_LAS unsigned*)(lds + (bufoff) + ldsw + _i * 8192), 16, 0, 0); } while (0)
; #define PG8_LDA(dst, b, h) do { _Pragma("unroll") for (int m = 0; m < 4; ++m) _Pragma("unroll") for (int k = 0; k < 2; ++k) dst[m][k] = *(const PG8_LAS bf16x8*)(lds + PG8_SA(b, h) + aoff + m * 2048 + k * 1024); } while (0)
; #define PG8_LDB(dst, b, h) do { _Pragma("unroll") for (int n = 0; n < 2; ++n) _Pragma("unroll") for (int k = 0; k < 2; ++k) dst[n][k] = *(const PG8_LAS bf16x8*)(lds + PG8_SB(b, h) + boff + n * 2048 + k * 1024); } while (0)
; #define PG8_MMA(ai, bj, At, Bt) do { __builtin_amdgcn_s_setprio(1); _Pragma("unroll") for (int m = 0; m < 4; ++m) _Pragma("unroll") for (int n = 0; n < 2; ++n) _Pragma("unroll") for (int k = 0; k < 2; ++k) \
;         acc[ai][bj][m][n] = __builtin_amdgcn_mfma_f32_16x16x32_bf16(Bt[n][k], At[m][k], acc[ai][bj][m][n], 0, 0, 0); __builtin_amdgcn_s_setprio(0); } while (0)
; #define PG8_WAIT_V(n) asm volatile("s_waitcnt vmcnt(" #n ")" ::: "memory")
; #define PG8_WAIT_L(n) asm volatile("s_waitcnt lgkmcnt(" #n ")" ::: "memory")
; #define PG8_BAR __builtin_amdgcn_s_barrier()
; #define PG8_SCHED __builtin_amdgcn_sched_barrier(0)
; template <class Epi, class Sched, bool ALIGN_EPI = false, bool SP2 = false>
; __device__ __forceinline__ void gemm_phase(PG8_LAS unsigned char* lds, const Gemm g, const Sched& S, const Epi& E, int tid_in) {
;     ...
;             PG8_LDB(B0, 0, 0); PG8_LDB(B1, 0, 1); PG8_SCHED; PG8_LDA(At, 0, 0); PG8_STAGE(PG8_SA(1, 1), a1 + hstepA, voffA);
;             PG8_WAIT_V(8); PG8_WAIT_L(0); PG8_BAR; PG8_MMA(0, 0, At, B0); PG8_MMA(0, 1, At, B1); PG8_BAR; PG8_SCHED;
;             PG8_LDA(At, 0, 1); PG8_STAGE(PG8_SB(0, 0), b2, voffB); PG8_STAGE(PG8_SB(0, 1), b2 + hstep, voffB); PG8_STAGE(PG8_SA(0, 0), a2, voffA);
;             PG8_WAIT_V(8); PG8_WAIT_L(0); PG8_BAR; PG8_MMA(1, 0, At, B0); PG8_MMA(1, 1, At, B1); PG8_BAR; PG8_SCHED;
.Lprio_skip542:
.LBB0_542:
	s_add_i32 s57, s15, 2
	s_add_u32 s54, s52, 0x80
	s_addc_u32 s55, s53, 0
	s_add_i32 s81, 0, 0x10000
	s_cmp_eq_u32 s70, s15
	s_cselect_b32 s55, s41, s55
	s_cselect_b32 s54, s40, s54
	v_add_u32_e32 v148, s81, v151
	s_cselect_b32 s59, s51, s13
	s_cselect_b32 s58, s50, s12
	s_add_i32 s15, 0, 0x14000
	ds_read_b128 v[140:143], v148
	ds_read_b128 v[144:147], v148 offset:1024
	ds_read_b128 v[154:157], v148 offset:2048
	ds_read_b128 v[158:161], v148 offset:3072
	v_add_u32_e32 v148, s15, v151
	ds_read_b128 v[162:165], v148
	ds_read_b128 v[166:169], v148 offset:1024
	ds_read_b128 v[170:173], v148 offset:2048
	ds_read_b128 v[174:177], v148 offset:3072
	v_lshl_add_u64 v[148:149], s[52:53], 0, v[136:137]
	s_add_i32 m0, s62, 0xc000
	s_cmp_eq_u32 s98, 2
	s_cbranch_scc1 .Lhalf_r0
	ds_read_b128 v[178:181], v153
	ds_read_b128 v[182:185], v153 offset:1024
	ds_read_b128 v[186:189], v153 offset:2048
	ds_read_b128 v[190:193], v153 offset:3072
	ds_read_b128 v[204:207], v153 offset:4096
	ds_read_b128 v[208:211], v153 offset:5120
	ds_read_b128 v[212:215], v153 offset:6144
	ds_read_b128 v[216:219], v153 offset:7168
.Lhalf_r0:
	global_load_lds_dwordx4 v[148:149], off
	v_lshl_add_u64 v[148:149], s[52:53], 0, v[138:139]
	s_add_i32 m0, s62, 0xe000
	s_nop 0
	global_load_lds_dwordx4 v[148:149], off
	s_waitcnt vmcnt(8)
	s_waitcnt lgkmcnt(0)
	s_barrier
	s_waitcnt lgkmcnt(0)
	s_cmp_eq_u32 s98, 2
	s_cbranch_scc1 .Lhalf_m0
	v_mfma_f32_16x16x32_bf16 v[126:129], v[140:143], v[178:181], v[126:129]
	v_mfma_f32_16x16x32_bf16 v[122:125], v[154:157], v[178:181], v[122:125]
	v_mfma_f32_16x16x32_bf16 v[110:113], v[140:143], v[186:189], v[110:113]
	v_mfma_f32_16x16x32_bf16 v[106:109], v[154:157], v[186:189], v[106:109]
	v_mfma_f32_16x16x32_bf16 v[94:97], v[140:143], v[204:207], v[94:97]
	v_mfma_f32_16x16x32_bf16 v[90:93], v[154:157], v[204:207], v[90:93]
	v_mfma_f32_16x16x32_bf16 v[78:81], v[140:143], v[212:215], v[78:81]
	v_mfma_f32_16x16x32_bf16 v[74:77], v[154:157], v[212:215], v[74:77]
	v_mfma_f32_16x16x32_bf16 v[126:129], v[144:147], v[182:185], v[126:129]
	v_mfma_f32_16x16x32_bf16 v[122:125], v[158:161], v[182:185], v[122:125]
	v_mfma_f32_16x16x32_bf16 v[110:113], v[144:147], v[190:193], v[110:113]
	v_mfma_f32_16x16x32_bf16 v[106:109], v[158:161], v[190:193], v[106:109]
	v_mfma_f32_16x16x32_bf16 v[94:97], v[144:147], v[208:211], v[94:97]
	v_mfma_f32_16x16x32_bf16 v[90:93], v[158:161], v[208:211], v[90:93]
	v_mfma_f32_16x16x32_bf16 v[78:81], v[144:147], v[216:219], v[78:81]
	v_mfma_f32_16x16x32_bf16 v[74:77], v[158:161], v[216:219], v[74:77]
	v_mfma_f32_16x16x32_bf16 v[118:121], v[162:165], v[178:181], v[118:121]
	v_mfma_f32_16x16x32_bf16 v[114:117], v[170:173], v[178:181], v[114:117]
	v_mfma_f32_16x16x32_bf16 v[102:105], v[162:165], v[186:189], v[102:105]
	v_mfma_f32_16x16x32_bf16 v[98:101], v[170:173], v[186:189], v[98:101]
	v_mfma_f32_16x16x32_bf16 v[86:89], v[162:165], v[204:207], v[86:89]
	v_mfma_f32_16x16x32_bf16 v[82:85], v[170:173], v[204:207], v[82:85]
	v_mfma_f32_16x16x32_bf16 v[70:73], v[162:165], v[212:215], v[70:73]
	v_mfma_f32_16x16x32_bf16 v[66:69], v[170:173], v[212:215], v[66:69]
	v_mfma_f32_16x16x32_bf16 v[118:121], v[166:169], v[182:185], v[118:121]
	v_mfma_f32_16x16x32_bf16 v[114:117], v[174:177], v[182:185], v[114:117]
	v_mfma_f32_16x16x32_bf16 v[102:105], v[166:169], v[190:193], v[102:105]
	v_mfma_f32_16x16x32_bf16 v[98:101], v[174:177], v[190:193], v[98:101]
	v_mfma_f32_16x16x32_bf16 v[86:89], v[166:169], v[208:211], v[86:89]
	v_mfma_f32_16x16x32_bf16 v[82:85], v[174:177], v[208:211], v[82:85]
	v_mfma_f32_16x16x32_bf16 v[70:73], v[166:169], v[216:219], v[70:73]
	v_mfma_f32_16x16x32_bf16 v[66:69], v[174:177], v[216:219], v[66:69]
.Lhalf_m0:
	s_barrier
	s_add_i32 s81, s81, s2
	v_lshl_add_u64 v[148:149], s[58:59], 0, v[0:1]
	s_mov_b32 m0, s81
	s_cmp_eq_u32 s98, 1
	s_cbranch_scc1 .Lhalf_r1
	ds_read_b128 v[178:181], v153 offset:16384
	ds_read_b128 v[182:185], v153 offset:17408
	ds_read_b128 v[186:189], v153 offset:18432
	ds_read_b128 v[190:193], v153 offset:19456
	ds_read_b128 v[204:207], v153 offset:20480
	ds_read_b128 v[208:211], v153 offset:21504
	ds_read_b128 v[212:215], v153 offset:22528
	ds_read_b128 v[216:219], v153 offset:23552
.Lhalf_r1:
	global_load_lds_dwordx4 v[148:149], off
	s_add_i32 m0, s81, 0x2000
	v_lshl_add_u64 v[194:195], s[58:59], 0, v[134:135]
	s_add_u32 s58, s58, s22
	s_addc_u32 s59, s59, s23
	s_add_i32 s15, s15, s2
	global_load_lds_dwordx4 v[194:195], off
	v_lshl_add_u64 v[220:221], s[58:59], 0, v[0:1]
	s_mov_b32 m0, s15
	v_lshl_add_u64 v[222:223], s[58:59], 0, v[134:135]
	global_load_lds_dwordx4 v[220:221], off
	s_add_i32 m0, s15, 0x2000
	v_lshl_add_u64 v[224:225], s[54:55], 0, v[130:131]
	global_load_lds_dwordx4 v[222:223], off
	s_mov_b32 m0, s62
	v_lshl_add_u64 v[226:227], s[54:55], 0, v[132:133]
	global_load_lds_dwordx4 v[224:225], off
	s_mov_b32 m0, s63
	s_nop 0
	global_load_lds_dwordx4 v[226:227], off
	s_waitcnt vmcnt(8)
	s_waitcnt lgkmcnt(0)
	s_barrier
	s_waitcnt lgkmcnt(0)
	s_cmp_eq_u32 s98, 1
	s_cbranch_scc1 .Lhalf_m1
; #define PG8_STAGE(bufoff, gbase, voff) do { _Pragma("unroll") for (int _i = 0; _i < 2; ++_i) \
;         __builtin_amdgcn_global_load_lds((const unsigned*)((const char*)(gbase) + (voff)[_i]), (PG8_LAS unsigned*)(lds + (bufoff) + ldsw + _i * 8192), 16, 0, 0); } while (0)
; #define PG8_LDA(dst, b, h) do { _Pragma("unroll") for (int m = 0; m < 4; ++m) _Pragma("unroll") for (int k = 0; k < 2; ++k) dst[m][k] = *(const PG8_LAS bf16x8*)(lds + PG8_SA(b, h) + aoff + m * 2048 + k * 1024); } while (0)
; #define PG8_LDB(dst, b, h) do { _Pragma("unroll") for (int n = 0; n < 2; ++n) _Pragma("unroll") for (int k = 0; k < 2; ++k) dst[n][k] = *(const PG8_LAS bf16x8*)(lds + PG8_SB(b, h) + boff + n * 2048 + k * 1024); } while (0)
; #define PG8_MMA(ai, bj, At, Bt) do { __builtin_amdgcn_s_setprio(1); _Pragma("unroll") for (int m = 0; m < 4; ++m) _Pragma("unroll") for (int n = 0; n < 2; ++n) _Pragma("unroll") for (int k = 0; k < 2; ++k) \
;         acc[ai][bj][m][n] = __builtin_amdgcn_mfma_f32_16x16x32_bf16(Bt[n][k], At[m][k], acc[ai][bj][m][n], 0, 0, 0); __builtin_amdgcn_s_setprio(0); } while (0)
; #define PG8_WAIT_V(n) asm volatile("s_waitcnt vmcnt(" #n ")" ::: "memory")
; #define PG8_WAIT_L(n) asm volatile("s_waitcnt lgkmcnt(" #n ")" ::: "memory")
; #define PG8_BAR __builtin_amdgcn_s_barrier()
; #define PG8_SCHED __builtin_amdgcn_sched_barrier(0)
; template <class Epi, class Sched, bool ALIGN_EPI = false, bool SP2 = false>
; __device__ __forceinline__ void gemm_phase(PG8_LAS unsigned char* lds, const Gemm g, const Sched& S, const Epi& E, int tid_in) {
;     ...
;             PG8_WAIT_V(8); PG8_WAIT_L(0); PG8_BAR; PG8_MMA(1, 0, At, B0); PG8_MMA(1, 1, At, B1); PG8_BAR; PG8_SCHED;
;             PG8_LDB(B0, 1, 0); PG8_LDB(B1, 1, 1); PG8_SCHED; PG8_LDA(At, 1, 0); PG8_STAGE(PG8_SA(0, 1), a2 + hstepA, voffA);
;             PG8_WAIT_V(8); PG8_WAIT_L(0); PG8_BAR; PG8_MMA(0, 0, At, B0); PG8_MMA(0, 1, At, B1); PG8_BAR; PG8_SCHED;
;             PG8_LDA(At, 1, 1); PG8_STAGE(PG8_SB(1, 0), b3, voffB); PG8_STAGE(PG8_SB(1, 1), b3 + hstep, voffB); PG8_STAGE(PG8_SA(1, 0), a3, voffA);
	v_mfma_f32_16x16x32_bf16 v[62:65], v[140:143], v[178:181], v[62:65]
	v_mfma_f32_16x16x32_bf16 v[58:61], v[154:157], v[178:181], v[58:61]
	v_mfma_f32_16x16x32_bf16 v[46:49], v[140:143], v[186:189], v[46:49]
	v_mfma_f32_16x16x32_bf16 v[42:45], v[154:157], v[186:189], v[42:45]
	v_mfma_f32_16x16x32_bf16 v[30:33], v[140:143], v[204:207], v[30:33]
	v_mfma_f32_16x16x32_bf16 v[26:29], v[154:157], v[204:207], v[26:29]
	v_mfma_f32_16x16x32_bf16 v[14:17], v[140:143], v[212:215], v[14:17]
	v_mfma_f32_16x16x32_bf16 v[10:13], v[154:157], v[212:215], v[10:13]
	v_mfma_f32_16x16x32_bf16 v[62:65], v[144:147], v[182:185], v[62:65]
	v_mfma_f32_16x16x32_bf16 v[58:61], v[158:161], v[182:185], v[58:61]
	v_mfma_f32_16x16x32_bf16 v[46:49], v[144:147], v[190:193], v[46:49]
	v_mfma_f32_16x16x32_bf16 v[42:45], v[158:161], v[190:193], v[42:45]
	v_mfma_f32_16x16x32_bf16 v[30:33], v[144:147], v[208:211], v[30:33]
	v_mfma_f32_16x16x32_bf16 v[26:29], v[158:161], v[208:211], v[26:29]
	v_mfma_f32_16x16x32_bf16 v[14:17], v[144:147], v[216:219], v[14:17]
	v_mfma_f32_16x16x32_bf16 v[10:13], v[158:161], v[216:219], v[10:13]
	v_mfma_f32_16x16x32_bf16 v[54:57], v[162:165], v[178:181], v[54:57]
	v_mfma_f32_16x16x32_bf16 v[50:53], v[170:173], v[178:181], v[50:53]
	v_mfma_f32_16x16x32_bf16 v[38:41], v[162:165], v[186:189], v[38:41]
	v_mfma_f32_16x16x32_bf16 v[34:37], v[170:173], v[186:189], v[34:37]
	v_mfma_f32_16x16x32_bf16 v[22:25], v[162:165], v[204:207], v[22:25]
	v_mfma_f32_16x16x32_bf16 v[18:21], v[170:173], v[204:207], v[18:21]
	v_mfma_f32_16x16x32_bf16 v[6:9], v[162:165], v[212:215], v[6:9]
	v_mfma_f32_16x16x32_bf16 v[2:5], v[170:173], v[212:215], v[2:5]
	v_mfma_f32_16x16x32_bf16 v[54:57], v[166:169], v[182:185], v[54:57]
	v_mfma_f32_16x16x32_bf16 v[50:53], v[174:177], v[182:185], v[50:53]
	v_mfma_f32_16x16x32_bf16 v[38:41], v[166:169], v[190:193], v[38:41]
	v_mfma_f32_16x16x32_bf16 v[34:37], v[174:177], v[190:193], v[34:37]
	v_mfma_f32_16x16x32_bf16 v[22:25], v[166:169], v[208:211], v[22:25]
	v_mfma_f32_16x16x32_bf16 v[18:21], v[174:177], v[208:211], v[18:21]
	v_mfma_f32_16x16x32_bf16 v[6:9], v[166:169], v[216:219], v[6:9]
	v_mfma_f32_16x16x32_bf16 v[2:5], v[174:177], v[216:219], v[2:5]
.Lhalf_m1:
	s_barrier
	s_add_i32 s15, 0, 0x18000
	s_add_i32 s58, 0, 0x1c000
	v_add_u32_e32 v158, s15, v151
	v_add_u32_e32 v174, s58, v151
	ds_read_b128 v[140:143], v158
	ds_read_b128 v[144:147], v158 offset:1024
	ds_read_b128 v[154:157], v158 offset:2048
	ds_read_b128 v[158:161], v158 offset:3072
	ds_read_b128 v[162:165], v174
	ds_read_b128 v[166:169], v174 offset:1024
	ds_read_b128 v[170:173], v174 offset:2048
	ds_read_b128 v[174:177], v174 offset:3072
	s_add_u32 s54, s54, s22
	s_addc_u32 s55, s55, s23
	s_mov_b32 m0, s64
	v_lshl_add_u64 v[228:229], s[54:55], 0, v[130:131]
	s_cmp_eq_u32 s98, 2
	s_cbranch_scc1 .Lhalf_r2
	ds_read_b128 v[178:181], v153 offset:32768
	ds_read_b128 v[182:185], v153 offset:33792
	ds_read_b128 v[186:189], v153 offset:34816
	ds_read_b128 v[190:193], v153 offset:35840
	ds_read_b128 v[204:207], v153 offset:36864
	ds_read_b128 v[208:211], v153 offset:37888
	ds_read_b128 v[212:215], v153 offset:38912
	ds_read_b128 v[216:219], v153 offset:39936
.Lhalf_r2:
	global_load_lds_dwordx4 v[228:229], off
	v_lshl_add_u64 v[228:229], s[54:55], 0, v[132:133]
	s_mov_b32 m0, s65
	s_nop 0
	global_load_lds_dwordx4 v[228:229], off
	s_waitcnt vmcnt(8)
	s_waitcnt lgkmcnt(0)
	s_barrier
	s_waitcnt lgkmcnt(0)
	s_cmp_eq_u32 s98, 2
	s_cbranch_scc1 .Lhalf_m2
	v_mfma_f32_16x16x32_bf16 v[126:129], v[140:143], v[178:181], v[126:129]
	v_mfma_f32_16x16x32_bf16 v[122:125], v[154:157], v[178:181], v[122:125]
	v_mfma_f32_16x16x32_bf16 v[110:113], v[140:143], v[186:189], v[110:113]
	v_mfma_f32_16x16x32_bf16 v[106:109], v[154:157], v[186:189], v[106:109]
	v_mfma_f32_16x16x32_bf16 v[94:97], v[140:143], v[204:207], v[94:97]
	v_mfma_f32_16x16x32_bf16 v[90:93], v[154:157], v[204:207], v[90:93]
	v_mfma_f32_16x16x32_bf16 v[78:81], v[140:143], v[212:215], v[78:81]
	v_mfma_f32_16x16x32_bf16 v[74:77], v[154:157], v[212:215], v[74:77]
	v_mfma_f32_16x16x32_bf16 v[126:129], v[144:147], v[182:185], v[126:129]
	v_mfma_f32_16x16x32_bf16 v[122:125], v[158:161], v[182:185], v[122:125]
	v_mfma_f32_16x16x32_bf16 v[110:113], v[144:147], v[190:193], v[110:113]
	v_mfma_f32_16x16x32_bf16 v[106:109], v[158:161], v[190:193], v[106:109]
	v_mfma_f32_16x16x32_bf16 v[94:97], v[144:147], v[208:211], v[94:97]
	v_mfma_f32_16x16x32_bf16 v[90:93], v[158:161], v[208:211], v[90:93]
	v_mfma_f32_16x16x32_bf16 v[78:81], v[144:147], v[216:219], v[78:81]
	v_mfma_f32_16x16x32_bf16 v[74:77], v[158:161], v[216:219], v[74:77]
	v_mfma_f32_16x16x32_bf16 v[118:121], v[162:165], v[178:181], v[118:121]
	v_mfma_f32_16x16x32_bf16 v[114:117], v[170:173], v[178:181], v[114:117]
	v_mfma_f32_16x16x32_bf16 v[102:105], v[162:165], v[186:189], v[102:105]
	v_mfma_f32_16x16x32_bf16 v[98:101], v[170:173], v[186:189], v[98:101]
	v_mfma_f32_16x16x32_bf16 v[86:89], v[162:165], v[204:207], v[86:89]
	v_mfma_f32_16x16x32_bf16 v[82:85], v[170:173], v[204:207], v[82:85]
	v_mfma_f32_16x16x32_bf16 v[70:73], v[162:165], v[212:215], v[70:73]
	v_mfma_f32_16x16x32_bf16 v[66:69], v[170:173], v[212:215], v[66:69]
	v_mfma_f32_16x16x32_bf16 v[118:121], v[166:169], v[182:185], v[118:121]
	v_mfma_f32_16x16x32_bf16 v[114:117], v[174:177], v[182:185], v[114:117]
	v_mfma_f32_16x16x32_bf16 v[102:105], v[166:169], v[190:193], v[102:105]
	v_mfma_f32_16x16x32_bf16 v[98:101], v[174:177], v[190:193], v[98:101]
	v_mfma_f32_16x16x32_bf16 v[86:89], v[166:169], v[208:211], v[86:89]
	v_mfma_f32_16x16x32_bf16 v[82:85], v[174:177], v[208:211], v[82:85]
	v_mfma_f32_16x16x32_bf16 v[70:73], v[166:169], v[216:219], v[70:73]
	v_mfma_f32_16x16x32_bf16 v[66:69], v[174:177], v[216:219], v[66:69]
; #define PG8_STAGE(bufoff, gbase, voff) do { _Pragma("unroll") for (int _i = 0; _i < 2; ++_i) \
;         __builtin_amdgcn_global_load_lds((const unsigned*)((const char*)(gbase) + (voff)[_i]), (PG8_LAS unsigned*)(lds + (bufoff) + ldsw + _i * 8192), 16, 0, 0); } while (0)
; #define PG8_LDA(dst, b, h) do { _Pragma("unroll") for (int m = 0; m < 4; ++m) _Pragma("unroll") for (int k = 0; k < 2; ++k) dst[m][k] = *(const PG8_LAS bf16x8*)(lds + PG8_SA(b, h) + aoff + m * 2048 + k * 1024); } while (0)
; #define PG8_MMA(ai, bj, At, Bt) do { __builtin_amdgcn_s_setprio(1); _Pragma("unroll") for (int m = 0; m < 4; ++m) _Pragma("unroll") for (int n = 0; n < 2; ++n) _Pragma("unroll") for (int k = 0; k < 2; ++k) \
;         acc[ai][bj][m][n] = __builtin_amdgcn_mfma_f32_16x16x32_bf16(Bt[n][k], At[m][k], acc[ai][bj][m][n], 0, 0, 0); __builtin_amdgcn_s_setprio(0); } while (0)
; #define PG8_WAIT_V(n) asm volatile("s_waitcnt vmcnt(" #n ")" ::: "memory")
; #define PG8_WAIT_L(n) asm volatile("s_waitcnt lgkmcnt(" #n ")" ::: "memory")
; #define PG8_BAR __builtin_amdgcn_s_barrier()
; #define PG8_SCHED __builtin_amdgcn_sched_barrier(0)
; template <class Epi, class Sched, bool ALIGN_EPI = false, bool SP2 = false>
; __device__ __forceinline__ void gemm_phase(PG8_LAS unsigned char* lds, const Gemm g, const Sched& S, const Epi& E, int tid_in) {
;     ...
;             PG8_LDA(At, 1, 1); PG8_STAGE(PG8_SB(1, 0), b3, voffB); PG8_STAGE(PG8_SB(1, 1), b3 + hstep, voffB); PG8_STAGE(PG8_SA(1, 0), a3, voffA);
;             PG8_WAIT_V(8); PG8_WAIT_L(0); PG8_BAR; PG8_MMA(1, 0, At, B0); PG8_MMA(1, 1, At, B1); PG8_BAR; PG8_SCHED;
.Lhalf_m2:
	s_barrier
	s_add_i32 s15, s15, s2
	v_lshl_add_u64 v[148:149], v[148:149], 0, s[28:29]
	s_mov_b32 m0, s15
	s_cmp_eq_u32 s98, 1
	s_cbranch_scc1 .Lhalf_r3
	ds_read_b128 v[178:181], v153 offset:49152
	ds_read_b128 v[182:185], v153 offset:50176
	ds_read_b128 v[186:189], v153 offset:51200
	ds_read_b128 v[190:193], v153 offset:52224
	ds_read_b128 v[204:207], v153 offset:53248
	ds_read_b128 v[208:211], v153 offset:54272
	ds_read_b128 v[212:215], v153 offset:55296
	ds_read_b128 v[216:219], v153 offset:56320
.Lhalf_r3:
	global_load_lds_dwordx4 v[148:149], off
	v_lshl_add_u64 v[148:149], v[194:195], 0, s[28:29]
	s_add_i32 m0, s15, 0x2000
	s_add_i32 s15, s58, s2
	global_load_lds_dwordx4 v[148:149], off
	v_lshl_add_u64 v[148:149], v[220:221], 0, s[28:29]
	s_mov_b32 m0, s15
	s_nop 0
	global_load_lds_dwordx4 v[148:149], off
	v_lshl_add_u64 v[148:149], v[222:223], 0, s[28:29]
	s_add_i32 m0, s15, 0x2000
	s_nop 0
	global_load_lds_dwordx4 v[148:149], off
	v_lshl_add_u64 v[148:149], v[224:225], 0, s[28:29]
	s_mov_b32 m0, s66
	s_nop 0
	global_load_lds_dwordx4 v[148:149], off
	v_lshl_add_u64 v[148:149], v[226:227], 0, s[28:29]
	s_mov_b32 m0, s67
	s_nop 0
	global_load_lds_dwordx4 v[148:149], off
	s_waitcnt vmcnt(8)
	s_waitcnt lgkmcnt(0)
	s_barrier
	s_waitcnt lgkmcnt(0)
	s_cmp_eq_u32 s98, 1
	s_cbranch_scc1 .Lhalf_m3
	v_mfma_f32_16x16x32_bf16 v[62:65], v[140:143], v[178:181], v[62:65]
	v_mfma_f32_16x16x32_bf16 v[58:61], v[154:157], v[178:181], v[58:61]
	v_mfma_f32_16x16x32_bf16 v[46:49], v[140:143], v[186:189], v[46:49]
	v_mfma_f32_16x16x32_bf16 v[42:45], v[154:157], v[186:189], v[42:45]
	v_mfma_f32_16x16x32_bf16 v[30:33], v[140:143], v[204:207], v[30:33]
	v_mfma_f32_16x16x32_bf16 v[26:29], v[154:157], v[204:207], v[26:29]
	v_mfma_f32_16x16x32_bf16 v[14:17], v[140:143], v[212:215], v[14:17]
	v_mfma_f32_16x16x32_bf16 v[10:13], v[154:157], v[212:215], v[10:13]
	v_mfma_f32_16x16x32_bf16 v[62:65], v[144:147], v[182:185], v[62:65]
	v_mfma_f32_16x16x32_bf16 v[58:61], v[158:161], v[182:185], v[58:61]
	v_mfma_f32_16x16x32_bf16 v[46:49], v[144:147], v[190:193], v[46:49]
	v_mfma_f32_16x16x32_bf16 v[42:45], v[158:161], v[190:193], v[42:45]
	v_mfma_f32_16x16x32_bf16 v[30:33], v[144:147], v[208:211], v[30:33]
	v_mfma_f32_16x16x32_bf16 v[26:29], v[158:161], v[208:211], v[26:29]
	v_mfma_f32_16x16x32_bf16 v[14:17], v[144:147], v[216:219], v[14:17]
	v_mfma_f32_16x16x32_bf16 v[10:13], v[158:161], v[216:219], v[10:13]
	v_mfma_f32_16x16x32_bf16 v[54:57], v[162:165], v[178:181], v[54:57]
	v_mfma_f32_16x16x32_bf16 v[50:53], v[170:173], v[178:181], v[50:53]
	v_mfma_f32_16x16x32_bf16 v[38:41], v[162:165], v[186:189], v[38:41]
	v_mfma_f32_16x16x32_bf16 v[34:37], v[170:173], v[186:189], v[34:37]
	v_mfma_f32_16x16x32_bf16 v[22:25], v[162:165], v[204:207], v[22:25]
	v_mfma_f32_16x16x32_bf16 v[18:21], v[170:173], v[204:207], v[18:21]
	v_mfma_f32_16x16x32_bf16 v[6:9], v[162:165], v[212:215], v[6:9]
	v_mfma_f32_16x16x32_bf16 v[2:5], v[170:173], v[212:215], v[2:5]
	v_mfma_f32_16x16x32_bf16 v[54:57], v[166:169], v[182:185], v[54:57]
	v_mfma_f32_16x16x32_bf16 v[50:53], v[174:177], v[182:185], v[50:53]
	v_mfma_f32_16x16x32_bf16 v[38:41], v[166:169], v[190:193], v[38:41]
	v_mfma_f32_16x16x32_bf16 v[34:37], v[174:177], v[190:193], v[34:37]
	v_mfma_f32_16x16x32_bf16 v[22:25], v[166:169], v[208:211], v[22:25]
	v_mfma_f32_16x16x32_bf16 v[18:21], v[174:177], v[208:211], v[18:21]
	v_mfma_f32_16x16x32_bf16 v[6:9], v[166:169], v[216:219], v[6:9]
	v_mfma_f32_16x16x32_bf16 v[2:5], v[174:177], v[216:219], v[2:5]
.Lhalf_m3:
	s_barrier
	s_add_u32 s52, s52, 0x100
	s_addc_u32 s53, s53, 0
	s_add_u32 s12, s12, 0x100
	s_addc_u32 s13, s13, 0
	s_cmp_ge_i32 s57, s69
	s_mov_b32 s15, s57
	s_cbranch_scc0 .LBB0_542
	s_setprio 0
	s_movk_i32 s81, 0x4040

; #define PG8_WAIT_V(n) asm volatile("s_waitcnt vmcnt(" #n ")" ::: "memory")
; #define PG8_BAR __builtin_amdgcn_s_barrier()
;     __host__ __device__ bool next(int i, Unit& u) const {
;         const long L = (long)i * G + c; if (L >= nwg) return false;
;         int wgid = (int)L; { const int q = nwg / NXCD, r = nwg % NXCD, xcd = wgid % NXCD, off = wgid / NXCD; wgid = (xcd < r ? xcd * (q + 1) : r * (q + 1) + (xcd - r) * q) + off; }
;         const int nig = WGM * nN, gid = wgid / nig, fm = gid * WGM, gsz = (nM - fm) < WGM ? (nM - fm) : WGM;
;         u.pm = fm + ((wgid % nig) % gsz); u.pn = (wgid % nig) / gsz; return true;
; template <class Epi, class Sched, bool ALIGN_EPI = false, bool SP2 = false>
; __device__ __forceinline__ void gemm_phase(PG8_LAS unsigned char* lds, const Gemm g, const Sched& S, const Epi& E, int tid_in) {
;     ...
;     PG8_WAIT_V(0);
;     if constexpr (!ALIGN_EPI) { if (wr == 0) PG8_BAR; }
.LBB0_661:
	s_waitcnt vmcnt(0)
	s_cmp_lg_u32 s94, 0x100
	s_cbranch_scc1 .Lwarm_done
	s_and_b32 s78, s20, 0xff
	s_and_b32 s79, s96, 7
	s_cmp_ge_u32 s79, s78
	s_cbranch_scc1 .Lwarm_done
	s_lshr_b32 s80, s96, 3
	s_add_i32 s80, s80, -2
	s_cmp_gt_u32 s80, 7
	s_cbranch_scc1 .Lwarm_done
	s_lshr_b32 s81, s20, 3
	s_and_b32 s54, s20, 7
	s_mul_i32 s55, s79, s81
	s_min_u32 s54, s79, s54
	s_add_i32 s55, s55, s54
	s_lshr_b32 s54, s20, 8
	s_lshl_b32 s54, s54, 5
	s_add_i32 s55, s55, s54
	s_lshr_b32 s54, s55, 5
	s_and_b32 s55, s55, 31
	s_lshl_b32 s54, s54, 3
	s_sub_i32 s62, s60, s54
	s_min_i32 s62, s62, 8
	s_ff1_i32_b32 s63, s62
	s_lshr_b32 s64, s55, s63
	s_add_i32 s62, s62, -1
	s_and_b32 s55, s55, s62
	s_add_i32 s54, s54, s55
	s_lshr_b32 s65, s42, 3
	s_mul_i32 s55, s65, s80
	s_mul_i32 s62, s42, s54
	s_mul_hi_u32 s63, s42, s54
	s_mul_i32 s81, s43, s54
	s_add_i32 s63, s63, s81
	s_add_u32 s62, s62, s18
	s_addc_u32 s63, s63, s19
	s_add_u32 s62, s62, s55
	s_addc_u32 s63, s63, 0
	s_mul_i32 s68, s42, s64
	s_mul_hi_u32 s69, s42, s64
	s_mul_i32 s81, s43, s64
	s_add_i32 s69, s69, s81
	s_add_u32 s68, s68, s8
	s_addc_u32 s69, s69, s9
	s_add_u32 s68, s68, s55
	s_addc_u32 s69, s69, 0
	v_mbcnt_lo_u32_b32 v2, -1, 0
	v_mbcnt_hi_u32_b32 v2, -1, v2
	v_add_u32_e32 v2, s84, v2
	v_lshlrev_b32_e32 v2, 4, v2
	s_lshr_b32 s54, s65, 13

;     __host__ __device__ bool next(int i, Unit& u) const {
;     ...
;         int wgid = (int)L; { const int q = nwg / NXCD, r = nwg % NXCD, xcd = wgid % NXCD, off = wgid / NXCD; wgid = (xcd < r ? xcd * (q + 1) : r * (q + 1) + (xcd - r) * q) + off; }
;         const int nig = WGM * nN, gid = wgid / nig, fm = gid * WGM, gsz = (nM - fm) < WGM ? (nM - fm) : WGM;
;         u.pm = fm + ((wgid % nig) % gsz); u.pn = (wgid % nig) / gsz; return true;
.Lpre1_real:
	s_cmp_eq_u32 s83, 6
	s_cbranch_scc0 .Lpre1_done
	s_movk_i32 s98, 0x500
	s_and_b32 s100, s96, 7
	s_cmp_lg_u32 s100, 0
	s_cbranch_scc1 .Lpre1_done
	s_lshr_b32 s101, s96, 3
	s_add_i32 s101, s101, -10
	s_cmp_gt_u32 s101, 19
	s_cbranch_scc1 .Lpre1_done
	s_and_b32 s100, s101, 7
	s_lshr_b32 s101, s101, 3
	s_addk_i32 s101, 0xa0
	s_mul_i32 s2, s100, 0xa2
	s_min_u32 s100, s100, 4
	s_add_i32 s2, s2, s100
	s_add_i32 s2, s2, s101
	s_mul_hi_u32 s63, s2, 0x66666667
	s_lshr_b32 s63, s63, 6
	s_mul_i32 s100, s63, 0xa0
	s_sub_i32 s100, s2, s100
	s_lshl_b32 s63, s63, 3
	s_cmp_eq_u32 s63, 0x40
	s_cbranch_scc1 .Lpre1_g8
	s_lshr_b32 s2, s100, 3
	s_and_b32 s100, s100, 7
	s_add_i32 s63, s63, s100
	s_branch .Lpre1_done

; __global__ void __launch_bounds__(512, 2) fwd_mega(Args a_) {
;     ...
;         int kind = 15, slab = 0;
;         if (ph == 0) kind = 0;
;         else if (ph <= 10) { const int q = (ph - 1) % 5; slab = (ph - 1) / 5; kind = q == 0 ? 1 : (q == 1 ? 14 : (q == 2 ? 2 : (q == 3 ? 3 : 4))); }
;         else if (ph == 11) kind = 5; else if (ph == 12) kind = 6;
;         else if (ph <= 26) { kind = 7 + (ph - 13) % 7; slab = (ph - 13) / 7; }
;         else if (ph == 27) { kind = 5; slab = 1; } else if (ph == 28) { kind = 6; slab = 1; }
.Lpre_chk:
	s_and_b32 s101, s96, 7
	s_cmp_gt_u32 s101, 2
	s_cbranch_scc1 .Lpre_none
	s_lshr_b32 s101, s96, 3
	s_add_i32 s101, s101, -10
	s_cmp_gt_u32 s101, 21
	s_cbranch_scc1 .Lpre_none
	s_mov_b32 s99, 1
	s_mov_b32 s65, 5
	s_mov_b32 s40, s100

; __global__ void __launch_bounds__(512, 2) fwd_mega(Args a_) {
;     ...
;         int kind = 15, slab = 0;
;         if (ph == 0) kind = 0;
;         else if (ph <= 10) { const int q = (ph - 1) % 5; slab = (ph - 1) / 5; kind = q == 0 ? 1 : (q == 1 ? 14 : (q == 2 ? 2 : (q == 3 ? 3 : 4))); }
;         else if (ph == 11) kind = 5; else if (ph == 12) kind = 6;
;         else if (ph <= 26) { kind = 7 + (ph - 13) % 7; slab = (ph - 13) / 7; }
;         else if (ph == 27) { kind = 5; slab = 1; } else if (ph == 28) { kind = 6; slab = 1; }
.Lpre_chk1:
	s_and_b32 s101, s96, 7
	s_cmp_lg_u32 s101, 0
	s_cbranch_scc1 .Lpre_none
	s_lshr_b32 s101, s96, 3
	s_add_i32 s101, s101, -10
	s_cmp_gt_u32 s101, 19
	s_cbranch_scc1 .Lpre_none
	s_mov_b32 s99, 1
	s_mov_b32 s65, 1
	s_mov_b32 s40, 1
	s_branch .Lpre_go
